# peeled first k-iteration also in PROJ and RES GEMM loops
# baseline (speedup 1.0000x reference)
.LBB0_808:
	s_ashr_i32 s21, s20, 31
	s_lshl_b64 s[22:23], s[20:21], 19
	v_readlane_b32 s24, v254, 28
	v_readlane_b32 s25, v254, 29
	s_add_u32 s22, s24, s22
	s_addc_u32 s23, s25, s23
	s_and_b64 s[24:25], s[4:5], exec
	s_cselect_b32 s7, s23, s9
	s_cselect_b32 s21, s22, s8
	s_ashr_i32 s19, s18, 31
	s_lshl_b64 s[24:25], s[18:19], 19
	s_add_u32 s24, s34, s24
	s_addc_u32 s25, s35, s25
	s_and_b64 s[30:31], s[4:5], exec
	s_cselect_b32 s19, s25, s29
	s_cselect_b32 s27, s24, s28
	s_add_u32 s8, s8, 0x40080
	s_addc_u32 s9, s9, 0
	s_add_u32 s53, s28, 0x100
	s_addc_u32 s54, s29, 0
	s_mov_b32 s55, -2
	s_add_u32 s28, s8, 0xfffc0080
	s_addc_u32 s29, s9, -1
	s_add_i32 s56, 0, 0x10000
	s_cmp_eq_u32 s55, 12
	s_cselect_b32 s31, s7, s29
	s_cselect_b32 s30, s21, s28
	s_cselect_b32 s29, s19, s54
	s_cselect_b32 s28, s27, s53
	s_add_i32 s58, 0, 0x14000
	v_add_u32_e32 v142, s56, v224
	v_add_u32_e32 v162, s58, v224
	ds_read_b128 v[130:133], v142
	ds_read_b128 v[134:137], v142 offset:1024
	ds_read_b128 v[138:141], v142 offset:2048
	ds_read_b128 v[142:145], v142 offset:3072
	ds_read_b128 v[146:149], v162
	ds_read_b128 v[150:153], v162 offset:1024
	ds_read_b128 v[176:179], v162 offset:2048
	ds_read_b128 v[180:183], v162 offset:3072
	v_lshl_add_u64 v[162:163], s[8:9], 0, v[172:173]
	s_add_i32 m0, s37, 0xc000
	ds_read_b128 v[184:187], v226
	ds_read_b128 v[188:191], v226 offset:1024
	ds_read_b128 v[192:195], v226 offset:2048
	ds_read_b128 v[196:199], v226 offset:3072
	ds_read_b128 v[200:203], v226 offset:4096
	ds_read_b128 v[204:207], v226 offset:5120
	ds_read_b128 v[228:231], v226 offset:6144
	ds_read_b128 v[232:235], v226 offset:7168
	global_load_lds_dwordx4 v[162:163], off
	v_lshl_add_u64 v[162:163], s[8:9], 0, v[174:175]
	s_add_i32 m0, s37, 0xe000
	s_nop 0
	global_load_lds_dwordx4 v[162:163], off
	s_waitcnt vmcnt(16)
	s_waitcnt lgkmcnt(0)
	s_barrier
	s_setprio 1
	s_waitcnt lgkmcnt(0)
	v_mfma_f32_16x16x32_bf16 v[126:129], v[130:133], v[184:187], 0
	v_mfma_f32_16x16x32_bf16 v[122:125], v[138:141], v[184:187], 0
	v_mfma_f32_16x16x32_bf16 v[110:113], v[130:133], v[192:195], 0
	v_mfma_f32_16x16x32_bf16 v[106:109], v[138:141], v[192:195], 0
	v_mfma_f32_16x16x32_bf16 v[94:97], v[130:133], v[200:203], 0
	v_mfma_f32_16x16x32_bf16 v[90:93], v[138:141], v[200:203], 0
	v_mfma_f32_16x16x32_bf16 v[78:81], v[130:133], v[228:231], 0
	v_mfma_f32_16x16x32_bf16 v[74:77], v[138:141], v[228:231], 0
	v_mfma_f32_16x16x32_bf16 v[126:129], v[134:137], v[188:191], v[126:129]
	v_mfma_f32_16x16x32_bf16 v[122:125], v[142:145], v[188:191], v[122:125]
	v_mfma_f32_16x16x32_bf16 v[110:113], v[134:137], v[196:199], v[110:113]
	v_mfma_f32_16x16x32_bf16 v[106:109], v[142:145], v[196:199], v[106:109]
	v_mfma_f32_16x16x32_bf16 v[94:97], v[134:137], v[204:207], v[94:97]
	v_mfma_f32_16x16x32_bf16 v[90:93], v[142:145], v[204:207], v[90:93]
	v_mfma_f32_16x16x32_bf16 v[78:81], v[134:137], v[232:235], v[78:81]
	v_mfma_f32_16x16x32_bf16 v[74:77], v[142:145], v[232:235], v[74:77]
	s_setprio 0
	s_setprio 1
	v_mfma_f32_16x16x32_bf16 v[118:121], v[146:149], v[184:187], 0
	v_mfma_f32_16x16x32_bf16 v[114:117], v[176:179], v[184:187], 0
	v_mfma_f32_16x16x32_bf16 v[102:105], v[146:149], v[192:195], 0
	v_mfma_f32_16x16x32_bf16 v[98:101], v[176:179], v[192:195], 0
	v_mfma_f32_16x16x32_bf16 v[86:89], v[146:149], v[200:203], 0
	v_mfma_f32_16x16x32_bf16 v[82:85], v[176:179], v[200:203], 0
	v_mfma_f32_16x16x32_bf16 v[70:73], v[146:149], v[228:231], 0
	v_mfma_f32_16x16x32_bf16 v[66:69], v[176:179], v[228:231], 0
	v_mfma_f32_16x16x32_bf16 v[118:121], v[150:153], v[188:191], v[118:121]
	v_mfma_f32_16x16x32_bf16 v[114:117], v[180:183], v[188:191], v[114:117]
	v_mfma_f32_16x16x32_bf16 v[102:105], v[150:153], v[196:199], v[102:105]
	v_mfma_f32_16x16x32_bf16 v[98:101], v[180:183], v[196:199], v[98:101]
	v_mfma_f32_16x16x32_bf16 v[86:89], v[150:153], v[204:207], v[86:89]
	v_mfma_f32_16x16x32_bf16 v[82:85], v[180:183], v[204:207], v[82:85]
	v_mfma_f32_16x16x32_bf16 v[70:73], v[150:153], v[232:235], v[70:73]
	v_mfma_f32_16x16x32_bf16 v[66:69], v[180:183], v[232:235], v[66:69]
	s_setprio 0
	s_barrier
	s_add_i32 s56, s56, s36
	v_lshl_add_u64 v[162:163], s[28:29], 0, v[0:1]
	s_mov_b32 m0, s56
	ds_read_b128 v[184:187], v226 offset:16384
	ds_read_b128 v[188:191], v226 offset:17408
	ds_read_b128 v[192:195], v226 offset:18432
	ds_read_b128 v[196:199], v226 offset:19456
	ds_read_b128 v[200:203], v226 offset:20480
	ds_read_b128 v[204:207], v226 offset:21504
	ds_read_b128 v[228:231], v226 offset:22528
	ds_read_b128 v[232:235], v226 offset:23552
	global_load_lds_dwordx4 v[162:163], off
	s_add_i32 m0, s56, 0x2000
	s_add_u32 s56, s28, 0x40000
	v_lshl_add_u64 v[208:209], s[28:29], 0, v[158:159]
	s_addc_u32 s57, s29, 0
	s_add_i32 s58, s58, s36
	global_load_lds_dwordx4 v[208:209], off
	v_lshl_add_u64 v[214:215], s[56:57], 0, v[0:1]
	s_mov_b32 m0, s58
	v_lshl_add_u64 v[216:217], s[30:31], 0, v[156:157]
	global_load_lds_dwordx4 v[214:215], off
	v_lshl_add_u64 v[214:215], s[56:57], 0, v[158:159]
	s_add_i32 m0, s58, 0x2000
	s_nop 0
	global_load_lds_dwordx4 v[214:215], off
	v_lshl_add_u64 v[214:215], s[30:31], 0, v[154:155]
	s_mov_b32 m0, s37
	s_nop 0
	global_load_lds_dwordx4 v[214:215], off
	s_mov_b32 m0, s38
	s_nop 0
	global_load_lds_dwordx4 v[216:217], off
	s_cmp_eq_u32 s46, 1
	s_cbranch_scc1 .Lpj_peel_w8
	s_waitcnt vmcnt(16)
	s_branch .Lpj_peel_wj

.Lpj_peel_wj:
	s_waitcnt lgkmcnt(0)
	s_barrier
	s_setprio 1
	s_waitcnt lgkmcnt(0)
	v_mfma_f32_16x16x32_bf16 v[62:65], v[130:133], v[184:187], 0
	v_mfma_f32_16x16x32_bf16 v[58:61], v[138:141], v[184:187], 0
	v_mfma_f32_16x16x32_bf16 v[46:49], v[130:133], v[192:195], 0
	v_mfma_f32_16x16x32_bf16 v[42:45], v[138:141], v[192:195], 0
	v_mfma_f32_16x16x32_bf16 v[30:33], v[130:133], v[200:203], 0
	v_mfma_f32_16x16x32_bf16 v[26:29], v[138:141], v[200:203], 0
	v_mfma_f32_16x16x32_bf16 v[14:17], v[130:133], v[228:231], 0
	v_mfma_f32_16x16x32_bf16 v[10:13], v[138:141], v[228:231], 0
	v_mfma_f32_16x16x32_bf16 v[62:65], v[134:137], v[188:191], v[62:65]
	v_mfma_f32_16x16x32_bf16 v[58:61], v[142:145], v[188:191], v[58:61]
	v_mfma_f32_16x16x32_bf16 v[46:49], v[134:137], v[196:199], v[46:49]
	v_mfma_f32_16x16x32_bf16 v[42:45], v[142:145], v[196:199], v[42:45]
	v_mfma_f32_16x16x32_bf16 v[30:33], v[134:137], v[204:207], v[30:33]
	v_mfma_f32_16x16x32_bf16 v[26:29], v[142:145], v[204:207], v[26:29]
	v_mfma_f32_16x16x32_bf16 v[14:17], v[134:137], v[232:235], v[14:17]
	v_mfma_f32_16x16x32_bf16 v[10:13], v[142:145], v[232:235], v[10:13]
	s_setprio 0
	s_setprio 1
	v_mfma_f32_16x16x32_bf16 v[54:57], v[146:149], v[184:187], 0
	v_mfma_f32_16x16x32_bf16 v[50:53], v[176:179], v[184:187], 0
	v_mfma_f32_16x16x32_bf16 v[38:41], v[146:149], v[192:195], 0
	v_mfma_f32_16x16x32_bf16 v[34:37], v[176:179], v[192:195], 0
	v_mfma_f32_16x16x32_bf16 v[22:25], v[146:149], v[200:203], 0
	v_mfma_f32_16x16x32_bf16 v[18:21], v[176:179], v[200:203], 0
	v_mfma_f32_16x16x32_bf16 v[6:9], v[146:149], v[228:231], 0
	v_mfma_f32_16x16x32_bf16 v[2:5], v[176:179], v[228:231], 0
	v_mfma_f32_16x16x32_bf16 v[54:57], v[150:153], v[188:191], v[54:57]
	v_mfma_f32_16x16x32_bf16 v[50:53], v[180:183], v[188:191], v[50:53]
	v_mfma_f32_16x16x32_bf16 v[38:41], v[150:153], v[196:199], v[38:41]
	v_mfma_f32_16x16x32_bf16 v[34:37], v[180:183], v[196:199], v[34:37]
	v_mfma_f32_16x16x32_bf16 v[22:25], v[150:153], v[204:207], v[22:25]
	v_mfma_f32_16x16x32_bf16 v[18:21], v[180:183], v[204:207], v[18:21]
	v_mfma_f32_16x16x32_bf16 v[6:9], v[150:153], v[232:235], v[6:9]
	v_mfma_f32_16x16x32_bf16 v[2:5], v[180:183], v[232:235], v[2:5]
	s_setprio 0
	s_barrier
	s_add_i32 s56, 0, 0x18000
	s_add_i32 s57, 0, 0x1c000
	v_add_u32_e32 v142, s56, v224
	v_add_u32_e32 v164, s57, v224
	ds_read_b128 v[130:133], v142
	ds_read_b128 v[134:137], v142 offset:1024
	ds_read_b128 v[138:141], v142 offset:2048
	ds_read_b128 v[142:145], v142 offset:3072
	ds_read_b128 v[146:149], v164
	ds_read_b128 v[150:153], v164 offset:1024
	ds_read_b128 v[176:179], v164 offset:2048
	ds_read_b128 v[180:183], v164 offset:3072
	s_add_u32 s30, s30, 0x40000
	s_addc_u32 s31, s31, 0
	s_mov_b32 m0, s39
	v_lshl_add_u64 v[236:237], s[30:31], 0, v[154:155]
	ds_read_b128 v[184:187], v226 offset:32768
	ds_read_b128 v[188:191], v226 offset:33792
	ds_read_b128 v[192:195], v226 offset:34816
	ds_read_b128 v[196:199], v226 offset:35840
	ds_read_b128 v[200:203], v226 offset:36864
	ds_read_b128 v[204:207], v226 offset:37888
	ds_read_b128 v[228:231], v226 offset:38912
	ds_read_b128 v[232:235], v226 offset:39936
	global_load_lds_dwordx4 v[236:237], off
	v_lshl_add_u64 v[236:237], s[30:31], 0, v[156:157]
	s_mov_b32 m0, s40
	s_nop 0
	global_load_lds_dwordx4 v[236:237], off
	s_waitcnt vmcnt(8)
	s_waitcnt lgkmcnt(0)
	s_barrier
	s_setprio 1
	s_waitcnt lgkmcnt(0)
	v_mfma_f32_16x16x32_bf16 v[126:129], v[130:133], v[184:187], v[126:129]
	v_mfma_f32_16x16x32_bf16 v[122:125], v[138:141], v[184:187], v[122:125]
	v_mfma_f32_16x16x32_bf16 v[110:113], v[130:133], v[192:195], v[110:113]
	v_mfma_f32_16x16x32_bf16 v[106:109], v[138:141], v[192:195], v[106:109]
	v_mfma_f32_16x16x32_bf16 v[94:97], v[130:133], v[200:203], v[94:97]
	v_mfma_f32_16x16x32_bf16 v[90:93], v[138:141], v[200:203], v[90:93]
	v_mfma_f32_16x16x32_bf16 v[78:81], v[130:133], v[228:231], v[78:81]
	v_mfma_f32_16x16x32_bf16 v[74:77], v[138:141], v[228:231], v[74:77]
	v_mfma_f32_16x16x32_bf16 v[126:129], v[134:137], v[188:191], v[126:129]
	v_mfma_f32_16x16x32_bf16 v[122:125], v[142:145], v[188:191], v[122:125]
	v_mfma_f32_16x16x32_bf16 v[110:113], v[134:137], v[196:199], v[110:113]
	v_mfma_f32_16x16x32_bf16 v[106:109], v[142:145], v[196:199], v[106:109]
	v_mfma_f32_16x16x32_bf16 v[94:97], v[134:137], v[204:207], v[94:97]
	v_mfma_f32_16x16x32_bf16 v[90:93], v[142:145], v[204:207], v[90:93]
	v_mfma_f32_16x16x32_bf16 v[78:81], v[134:137], v[232:235], v[78:81]
	v_mfma_f32_16x16x32_bf16 v[74:77], v[142:145], v[232:235], v[74:77]
	s_setprio 0
	s_setprio 1
	v_mfma_f32_16x16x32_bf16 v[118:121], v[146:149], v[184:187], v[118:121]
	v_mfma_f32_16x16x32_bf16 v[114:117], v[176:179], v[184:187], v[114:117]
	v_mfma_f32_16x16x32_bf16 v[102:105], v[146:149], v[192:195], v[102:105]
	v_mfma_f32_16x16x32_bf16 v[98:101], v[176:179], v[192:195], v[98:101]
	v_mfma_f32_16x16x32_bf16 v[86:89], v[146:149], v[200:203], v[86:89]
	v_mfma_f32_16x16x32_bf16 v[82:85], v[176:179], v[200:203], v[82:85]
	v_mfma_f32_16x16x32_bf16 v[70:73], v[146:149], v[228:231], v[70:73]
	v_mfma_f32_16x16x32_bf16 v[66:69], v[176:179], v[228:231], v[66:69]
	v_mfma_f32_16x16x32_bf16 v[118:121], v[150:153], v[188:191], v[118:121]
	v_mfma_f32_16x16x32_bf16 v[114:117], v[180:183], v[188:191], v[114:117]
	v_mfma_f32_16x16x32_bf16 v[102:105], v[150:153], v[196:199], v[102:105]
	v_mfma_f32_16x16x32_bf16 v[98:101], v[180:183], v[196:199], v[98:101]
	v_mfma_f32_16x16x32_bf16 v[86:89], v[150:153], v[204:207], v[86:89]
	v_mfma_f32_16x16x32_bf16 v[82:85], v[180:183], v[204:207], v[82:85]
	v_mfma_f32_16x16x32_bf16 v[70:73], v[150:153], v[232:235], v[70:73]
	v_mfma_f32_16x16x32_bf16 v[66:69], v[180:183], v[232:235], v[66:69]
	s_setprio 0
	s_barrier
	s_add_i32 s30, s56, s36
	v_lshl_add_u64 v[162:163], v[162:163], 0, s[86:87]
	s_mov_b32 m0, s30
	ds_read_b128 v[184:187], v226 offset:49152
	ds_read_b128 v[188:191], v226 offset:50176
	ds_read_b128 v[192:195], v226 offset:51200
	ds_read_b128 v[196:199], v226 offset:52224
	ds_read_b128 v[200:203], v226 offset:53248
	ds_read_b128 v[204:207], v226 offset:54272
	ds_read_b128 v[228:231], v226 offset:55296
	ds_read_b128 v[232:235], v226 offset:56320
	global_load_lds_dwordx4 v[162:163], off
	s_add_i32 m0, s30, 0x2000
	s_add_u32 s28, s28, 0x40080
	v_lshl_add_u64 v[162:163], v[208:209], 0, s[86:87]
	s_addc_u32 s29, s29, 0
	s_add_i32 s30, s57, s36
	global_load_lds_dwordx4 v[162:163], off
	v_lshl_add_u64 v[162:163], s[28:29], 0, v[0:1]
	s_mov_b32 m0, s30
	s_nop 0
	global_load_lds_dwordx4 v[162:163], off
	v_lshl_add_u64 v[162:163], s[28:29], 0, v[158:159]
	s_add_i32 m0, s30, 0x2000
	s_nop 0
	global_load_lds_dwordx4 v[162:163], off
	v_lshl_add_u64 v[162:163], v[214:215], 0, s[86:87]
	s_mov_b32 m0, s44
	s_nop 0
	global_load_lds_dwordx4 v[162:163], off
	v_lshl_add_u64 v[162:163], v[216:217], 0, s[86:87]
	s_mov_b32 m0, s45
	s_nop 0
	global_load_lds_dwordx4 v[162:163], off
	s_waitcnt vmcnt(8)
	s_waitcnt lgkmcnt(0)
	s_barrier
	s_setprio 1
	s_waitcnt lgkmcnt(0)
	v_mfma_f32_16x16x32_bf16 v[62:65], v[130:133], v[184:187], v[62:65]
	v_mfma_f32_16x16x32_bf16 v[58:61], v[138:141], v[184:187], v[58:61]
	v_mfma_f32_16x16x32_bf16 v[46:49], v[130:133], v[192:195], v[46:49]
	v_mfma_f32_16x16x32_bf16 v[42:45], v[138:141], v[192:195], v[42:45]
	v_mfma_f32_16x16x32_bf16 v[30:33], v[130:133], v[200:203], v[30:33]
	v_mfma_f32_16x16x32_bf16 v[26:29], v[138:141], v[200:203], v[26:29]
	v_mfma_f32_16x16x32_bf16 v[14:17], v[130:133], v[228:231], v[14:17]
	v_mfma_f32_16x16x32_bf16 v[10:13], v[138:141], v[228:231], v[10:13]
	v_mfma_f32_16x16x32_bf16 v[62:65], v[134:137], v[188:191], v[62:65]
	v_mfma_f32_16x16x32_bf16 v[58:61], v[142:145], v[188:191], v[58:61]
	v_mfma_f32_16x16x32_bf16 v[46:49], v[134:137], v[196:199], v[46:49]
	v_mfma_f32_16x16x32_bf16 v[42:45], v[142:145], v[196:199], v[42:45]
	v_mfma_f32_16x16x32_bf16 v[30:33], v[134:137], v[204:207], v[30:33]
	v_mfma_f32_16x16x32_bf16 v[26:29], v[142:145], v[204:207], v[26:29]
	v_mfma_f32_16x16x32_bf16 v[14:17], v[134:137], v[232:235], v[14:17]
	v_mfma_f32_16x16x32_bf16 v[10:13], v[142:145], v[232:235], v[10:13]
	s_setprio 0
	s_setprio 1
	v_mfma_f32_16x16x32_bf16 v[54:57], v[146:149], v[184:187], v[54:57]
	v_mfma_f32_16x16x32_bf16 v[50:53], v[176:179], v[184:187], v[50:53]
	v_mfma_f32_16x16x32_bf16 v[38:41], v[146:149], v[192:195], v[38:41]
	v_mfma_f32_16x16x32_bf16 v[34:37], v[176:179], v[192:195], v[34:37]
	v_mfma_f32_16x16x32_bf16 v[22:25], v[146:149], v[200:203], v[22:25]
	v_mfma_f32_16x16x32_bf16 v[18:21], v[176:179], v[200:203], v[18:21]
	v_mfma_f32_16x16x32_bf16 v[6:9], v[146:149], v[228:231], v[6:9]
	v_mfma_f32_16x16x32_bf16 v[2:5], v[176:179], v[228:231], v[2:5]
	v_mfma_f32_16x16x32_bf16 v[54:57], v[150:153], v[188:191], v[54:57]
	v_mfma_f32_16x16x32_bf16 v[50:53], v[180:183], v[188:191], v[50:53]
	v_mfma_f32_16x16x32_bf16 v[38:41], v[150:153], v[196:199], v[38:41]
	v_mfma_f32_16x16x32_bf16 v[34:37], v[180:183], v[196:199], v[34:37]
	v_mfma_f32_16x16x32_bf16 v[22:25], v[150:153], v[204:207], v[22:25]
	v_mfma_f32_16x16x32_bf16 v[18:21], v[180:183], v[204:207], v[18:21]
	v_mfma_f32_16x16x32_bf16 v[6:9], v[150:153], v[232:235], v[6:9]
	v_mfma_f32_16x16x32_bf16 v[2:5], v[180:183], v[232:235], v[2:5]
	s_setprio 0
	s_barrier
	s_add_i32 s55, s55, 2
	s_add_u32 s8, s8, 0x100
	s_addc_u32 s9, s9, 0
	s_add_u32 s53, s53, 0x100
	s_addc_u32 s54, s54, 0
	s_cmp_gt_u32 s55, 13
	s_cbranch_scc0 .LBB0_809

.LBB0_1343:
	s_add_u32 s6, s26, 0x80
	s_addc_u32 s7, s27, 0
	s_add_u32 s26, s24, 0x100
	s_addc_u32 s27, s25, 0
	s_mov_b32 s24, 0
	s_add_i32 s47, s24, 2
	s_add_u32 s48, s6, 0x80
	s_addc_u32 s25, s7, 0
	s_add_i32 s50, 0, 0x10000
	s_cmp_eq_u32 s41, s24
	s_cselect_b32 s25, s21, s25
	s_cselect_b32 s24, s20, s48
	s_cselect_b32 s49, s23, s27
	s_cselect_b32 s48, s22, s26
	s_add_i32 s51, 0, 0x14000
	v_add_u32_e32 v142, s50, v197
	v_add_u32_e32 v162, s51, v197
	ds_read_b128 v[122:125], v142
	ds_read_b128 v[134:137], v142 offset:1024
	ds_read_b128 v[138:141], v142 offset:2048
	ds_read_b128 v[142:145], v142 offset:3072
	ds_read_b128 v[146:149], v162
	ds_read_b128 v[150:153], v162 offset:1024
	ds_read_b128 v[154:157], v162 offset:2048
	ds_read_b128 v[178:181], v162 offset:3072
	v_lshl_add_u64 v[162:163], s[6:7], 0, v[174:175]
	s_add_i32 m0, s31, 0xc000
	ds_read_b128 v[182:185], v199
	ds_read_b128 v[186:189], v199 offset:1024
	ds_read_b128 v[190:193], v199 offset:2048
	ds_read_b128 v[200:203], v199 offset:3072
	ds_read_b128 v[204:207], v199 offset:4096
	ds_read_b128 v[224:227], v199 offset:5120
	ds_read_b128 v[228:231], v199 offset:6144
	ds_read_b128 v[232:235], v199 offset:7168
	global_load_lds_dwordx4 v[162:163], off
	v_lshl_add_u64 v[162:163], s[6:7], 0, v[176:177]
	s_add_i32 m0, s31, 0xe000
	s_nop 0
	global_load_lds_dwordx4 v[162:163], off
	s_waitcnt vmcnt(16)
	s_waitcnt lgkmcnt(0)
	s_barrier
	s_setprio 1
	s_waitcnt lgkmcnt(0)
	v_mfma_f32_16x16x32_bf16 v[130:133], v[122:125], v[182:185], 0
	v_mfma_f32_16x16x32_bf16 v[126:129], v[138:141], v[182:185], 0
	v_mfma_f32_16x16x32_bf16 v[110:113], v[122:125], v[190:193], 0
	v_mfma_f32_16x16x32_bf16 v[106:109], v[138:141], v[190:193], 0
	v_mfma_f32_16x16x32_bf16 v[94:97], v[122:125], v[204:207], 0
	v_mfma_f32_16x16x32_bf16 v[90:93], v[138:141], v[204:207], 0
	v_mfma_f32_16x16x32_bf16 v[78:81], v[122:125], v[228:231], 0
	v_mfma_f32_16x16x32_bf16 v[74:77], v[138:141], v[228:231], 0
	v_mfma_f32_16x16x32_bf16 v[130:133], v[134:137], v[186:189], v[130:133]
	v_mfma_f32_16x16x32_bf16 v[126:129], v[142:145], v[186:189], v[126:129]
	v_mfma_f32_16x16x32_bf16 v[110:113], v[134:137], v[200:203], v[110:113]
	v_mfma_f32_16x16x32_bf16 v[106:109], v[142:145], v[200:203], v[106:109]
	v_mfma_f32_16x16x32_bf16 v[94:97], v[134:137], v[224:227], v[94:97]
	v_mfma_f32_16x16x32_bf16 v[90:93], v[142:145], v[224:227], v[90:93]
	v_mfma_f32_16x16x32_bf16 v[78:81], v[134:137], v[232:235], v[78:81]
	v_mfma_f32_16x16x32_bf16 v[74:77], v[142:145], v[232:235], v[74:77]
	s_setprio 0
	s_setprio 1
	v_mfma_f32_16x16x32_bf16 v[118:121], v[146:149], v[182:185], 0
	v_mfma_f32_16x16x32_bf16 v[114:117], v[154:157], v[182:185], 0
	v_mfma_f32_16x16x32_bf16 v[102:105], v[146:149], v[190:193], 0
	v_mfma_f32_16x16x32_bf16 v[98:101], v[154:157], v[190:193], 0
	v_mfma_f32_16x16x32_bf16 v[86:89], v[146:149], v[204:207], 0
	v_mfma_f32_16x16x32_bf16 v[82:85], v[154:157], v[204:207], 0
	v_mfma_f32_16x16x32_bf16 v[70:73], v[146:149], v[228:231], 0
	v_mfma_f32_16x16x32_bf16 v[66:69], v[154:157], v[228:231], 0
	v_mfma_f32_16x16x32_bf16 v[118:121], v[150:153], v[186:189], v[118:121]
	v_mfma_f32_16x16x32_bf16 v[114:117], v[178:181], v[186:189], v[114:117]
	v_mfma_f32_16x16x32_bf16 v[102:105], v[150:153], v[200:203], v[102:105]
	v_mfma_f32_16x16x32_bf16 v[98:101], v[178:181], v[200:203], v[98:101]
	v_mfma_f32_16x16x32_bf16 v[86:89], v[150:153], v[224:227], v[86:89]
	v_mfma_f32_16x16x32_bf16 v[82:85], v[178:181], v[224:227], v[82:85]
	v_mfma_f32_16x16x32_bf16 v[70:73], v[150:153], v[232:235], v[70:73]
	v_mfma_f32_16x16x32_bf16 v[66:69], v[178:181], v[232:235], v[66:69]
	s_setprio 0
	s_barrier
	s_add_i32 s50, s50, s30
	v_lshl_add_u64 v[162:163], s[48:49], 0, v[0:1]
	s_mov_b32 m0, s50
	ds_read_b128 v[182:185], v199 offset:16384
	ds_read_b128 v[186:189], v199 offset:17408
	ds_read_b128 v[190:193], v199 offset:18432
	ds_read_b128 v[200:203], v199 offset:19456
	ds_read_b128 v[204:207], v199 offset:20480
	ds_read_b128 v[224:227], v199 offset:21504
	ds_read_b128 v[228:231], v199 offset:22528
	ds_read_b128 v[232:235], v199 offset:23552
	global_load_lds_dwordx4 v[162:163], off
	s_add_i32 m0, s50, 0x2000
	v_lshl_add_u64 v[194:195], s[48:49], 0, v[160:161]
	s_add_u32 s48, s48, s28
	s_addc_u32 s49, s49, 0
	s_add_i32 s50, s51, s30
	global_load_lds_dwordx4 v[194:195], off
	v_lshl_add_u64 v[208:209], s[48:49], 0, v[0:1]
	s_mov_b32 m0, s50
	v_lshl_add_u64 v[214:215], s[48:49], 0, v[160:161]
	global_load_lds_dwordx4 v[208:209], off
	s_add_i32 m0, s50, 0x2000
	v_lshl_add_u64 v[216:217], s[24:25], 0, v[172:173]
	global_load_lds_dwordx4 v[214:215], off
	s_mov_b32 m0, s31
	v_lshl_add_u64 v[236:237], s[24:25], 0, v[170:171]
	global_load_lds_dwordx4 v[216:217], off
	s_mov_b32 m0, s34
	s_nop 0
	global_load_lds_dwordx4 v[236:237], off
	s_cmp_eq_u32 s42, 1
	s_cbranch_scc1 .Lrs_peel_w8
	s_waitcnt vmcnt(16)
	s_branch .Lrs_peel_wj

.Lrs_peel_wj:
	s_waitcnt lgkmcnt(0)
	s_barrier
	s_setprio 1
	s_waitcnt lgkmcnt(0)
	v_mfma_f32_16x16x32_bf16 v[62:65], v[122:125], v[182:185], 0
	v_mfma_f32_16x16x32_bf16 v[58:61], v[138:141], v[182:185], 0
	v_mfma_f32_16x16x32_bf16 v[46:49], v[122:125], v[190:193], 0
	v_mfma_f32_16x16x32_bf16 v[42:45], v[138:141], v[190:193], 0
	v_mfma_f32_16x16x32_bf16 v[30:33], v[122:125], v[204:207], 0
	v_mfma_f32_16x16x32_bf16 v[26:29], v[138:141], v[204:207], 0
	v_mfma_f32_16x16x32_bf16 v[14:17], v[122:125], v[228:231], 0
	v_mfma_f32_16x16x32_bf16 v[10:13], v[138:141], v[228:231], 0
	v_mfma_f32_16x16x32_bf16 v[62:65], v[134:137], v[186:189], v[62:65]
	v_mfma_f32_16x16x32_bf16 v[58:61], v[142:145], v[186:189], v[58:61]
	v_mfma_f32_16x16x32_bf16 v[46:49], v[134:137], v[200:203], v[46:49]
	v_mfma_f32_16x16x32_bf16 v[42:45], v[142:145], v[200:203], v[42:45]
	v_mfma_f32_16x16x32_bf16 v[30:33], v[134:137], v[224:227], v[30:33]
	v_mfma_f32_16x16x32_bf16 v[26:29], v[142:145], v[224:227], v[26:29]
	v_mfma_f32_16x16x32_bf16 v[14:17], v[134:137], v[232:235], v[14:17]
	v_mfma_f32_16x16x32_bf16 v[10:13], v[142:145], v[232:235], v[10:13]
	s_setprio 0
	s_setprio 1
	v_mfma_f32_16x16x32_bf16 v[54:57], v[146:149], v[182:185], 0
	v_mfma_f32_16x16x32_bf16 v[50:53], v[154:157], v[182:185], 0
	v_mfma_f32_16x16x32_bf16 v[38:41], v[146:149], v[190:193], 0
	v_mfma_f32_16x16x32_bf16 v[34:37], v[154:157], v[190:193], 0
	v_mfma_f32_16x16x32_bf16 v[22:25], v[146:149], v[204:207], 0
	v_mfma_f32_16x16x32_bf16 v[18:21], v[154:157], v[204:207], 0
	v_mfma_f32_16x16x32_bf16 v[6:9], v[146:149], v[228:231], 0
	v_mfma_f32_16x16x32_bf16 v[2:5], v[154:157], v[228:231], 0
	v_mfma_f32_16x16x32_bf16 v[54:57], v[150:153], v[186:189], v[54:57]
	v_mfma_f32_16x16x32_bf16 v[50:53], v[178:181], v[186:189], v[50:53]
	v_mfma_f32_16x16x32_bf16 v[38:41], v[150:153], v[200:203], v[38:41]
	v_mfma_f32_16x16x32_bf16 v[34:37], v[178:181], v[200:203], v[34:37]
	v_mfma_f32_16x16x32_bf16 v[22:25], v[150:153], v[224:227], v[22:25]
	v_mfma_f32_16x16x32_bf16 v[18:21], v[178:181], v[224:227], v[18:21]
	v_mfma_f32_16x16x32_bf16 v[6:9], v[150:153], v[232:235], v[6:9]
	v_mfma_f32_16x16x32_bf16 v[2:5], v[178:181], v[232:235], v[2:5]
	s_setprio 0
	s_barrier
	s_add_i32 s48, 0, 0x18000
	s_add_i32 s49, 0, 0x1c000
	v_add_u32_e32 v142, s48, v197
	v_add_u32_e32 v164, s49, v197
	ds_read_b128 v[122:125], v142
	ds_read_b128 v[134:137], v142 offset:1024
	ds_read_b128 v[138:141], v142 offset:2048
	ds_read_b128 v[142:145], v142 offset:3072
	ds_read_b128 v[146:149], v164
	ds_read_b128 v[150:153], v164 offset:1024
	ds_read_b128 v[154:157], v164 offset:2048
	ds_read_b128 v[178:181], v164 offset:3072
	s_add_u32 s24, s24, s10
	s_addc_u32 s25, s25, 0
	s_mov_b32 m0, s35
	v_lshl_add_u64 v[238:239], s[24:25], 0, v[172:173]
	ds_read_b128 v[182:185], v199 offset:32768
	ds_read_b128 v[186:189], v199 offset:33792
	ds_read_b128 v[190:193], v199 offset:34816
	ds_read_b128 v[200:203], v199 offset:35840
	ds_read_b128 v[204:207], v199 offset:36864
	ds_read_b128 v[224:227], v199 offset:37888
	ds_read_b128 v[228:231], v199 offset:38912
	ds_read_b128 v[232:235], v199 offset:39936
	global_load_lds_dwordx4 v[238:239], off
	v_lshl_add_u64 v[238:239], s[24:25], 0, v[170:171]
	s_mov_b32 m0, s36
	s_nop 0
	global_load_lds_dwordx4 v[238:239], off
	s_waitcnt vmcnt(8)
	s_waitcnt lgkmcnt(0)
	s_barrier
	s_setprio 1
	s_waitcnt lgkmcnt(0)
	v_mfma_f32_16x16x32_bf16 v[130:133], v[122:125], v[182:185], v[130:133]
	v_mfma_f32_16x16x32_bf16 v[126:129], v[138:141], v[182:185], v[126:129]
	v_mfma_f32_16x16x32_bf16 v[110:113], v[122:125], v[190:193], v[110:113]
	v_mfma_f32_16x16x32_bf16 v[106:109], v[138:141], v[190:193], v[106:109]
	v_mfma_f32_16x16x32_bf16 v[94:97], v[122:125], v[204:207], v[94:97]
	v_mfma_f32_16x16x32_bf16 v[90:93], v[138:141], v[204:207], v[90:93]
	v_mfma_f32_16x16x32_bf16 v[78:81], v[122:125], v[228:231], v[78:81]
	v_mfma_f32_16x16x32_bf16 v[74:77], v[138:141], v[228:231], v[74:77]
	v_mfma_f32_16x16x32_bf16 v[130:133], v[134:137], v[186:189], v[130:133]
	v_mfma_f32_16x16x32_bf16 v[126:129], v[142:145], v[186:189], v[126:129]
	v_mfma_f32_16x16x32_bf16 v[110:113], v[134:137], v[200:203], v[110:113]
	v_mfma_f32_16x16x32_bf16 v[106:109], v[142:145], v[200:203], v[106:109]
	v_mfma_f32_16x16x32_bf16 v[94:97], v[134:137], v[224:227], v[94:97]
	v_mfma_f32_16x16x32_bf16 v[90:93], v[142:145], v[224:227], v[90:93]
	v_mfma_f32_16x16x32_bf16 v[78:81], v[134:137], v[232:235], v[78:81]
	v_mfma_f32_16x16x32_bf16 v[74:77], v[142:145], v[232:235], v[74:77]
	s_setprio 0
	s_setprio 1
	v_mfma_f32_16x16x32_bf16 v[118:121], v[146:149], v[182:185], v[118:121]
	v_mfma_f32_16x16x32_bf16 v[114:117], v[154:157], v[182:185], v[114:117]
	v_mfma_f32_16x16x32_bf16 v[102:105], v[146:149], v[190:193], v[102:105]
	v_mfma_f32_16x16x32_bf16 v[98:101], v[154:157], v[190:193], v[98:101]
	v_mfma_f32_16x16x32_bf16 v[86:89], v[146:149], v[204:207], v[86:89]
	v_mfma_f32_16x16x32_bf16 v[82:85], v[154:157], v[204:207], v[82:85]
	v_mfma_f32_16x16x32_bf16 v[70:73], v[146:149], v[228:231], v[70:73]
	v_mfma_f32_16x16x32_bf16 v[66:69], v[154:157], v[228:231], v[66:69]
	v_mfma_f32_16x16x32_bf16 v[118:121], v[150:153], v[186:189], v[118:121]
	v_mfma_f32_16x16x32_bf16 v[114:117], v[178:181], v[186:189], v[114:117]
	v_mfma_f32_16x16x32_bf16 v[102:105], v[150:153], v[200:203], v[102:105]
	v_mfma_f32_16x16x32_bf16 v[98:101], v[178:181], v[200:203], v[98:101]
	v_mfma_f32_16x16x32_bf16 v[86:89], v[150:153], v[224:227], v[86:89]
	v_mfma_f32_16x16x32_bf16 v[82:85], v[178:181], v[224:227], v[82:85]
	v_mfma_f32_16x16x32_bf16 v[70:73], v[150:153], v[232:235], v[70:73]
	v_mfma_f32_16x16x32_bf16 v[66:69], v[178:181], v[232:235], v[66:69]
	s_setprio 0
	s_barrier
	s_add_i32 s24, s48, s30
	v_lshl_add_u64 v[162:163], v[162:163], 0, s[86:87]
	s_mov_b32 m0, s24
	ds_read_b128 v[182:185], v199 offset:49152
	ds_read_b128 v[186:189], v199 offset:50176
	ds_read_b128 v[190:193], v199 offset:51200
	ds_read_b128 v[200:203], v199 offset:52224
	ds_read_b128 v[204:207], v199 offset:53248
	ds_read_b128 v[224:227], v199 offset:54272
	ds_read_b128 v[228:231], v199 offset:55296
	ds_read_b128 v[232:235], v199 offset:56320
	global_load_lds_dwordx4 v[162:163], off
	v_lshl_add_u64 v[162:163], v[194:195], 0, s[86:87]
	s_add_i32 m0, s24, 0x2000
	s_add_i32 s24, s49, s30
	global_load_lds_dwordx4 v[162:163], off
	v_lshl_add_u64 v[162:163], v[208:209], 0, s[86:87]
	s_mov_b32 m0, s24
	s_nop 0
	global_load_lds_dwordx4 v[162:163], off
	v_lshl_add_u64 v[162:163], v[214:215], 0, s[86:87]
	s_add_i32 m0, s24, 0x2000
	s_nop 0
	global_load_lds_dwordx4 v[162:163], off
	v_lshl_add_u64 v[162:163], v[216:217], 0, s[86:87]
	s_mov_b32 m0, s37
	s_nop 0
	global_load_lds_dwordx4 v[162:163], off
	v_lshl_add_u64 v[162:163], v[236:237], 0, s[86:87]
	s_mov_b32 m0, s38
	s_nop 0
	global_load_lds_dwordx4 v[162:163], off
	s_waitcnt vmcnt(8)
	s_waitcnt lgkmcnt(0)
	s_barrier
	s_setprio 1
	s_waitcnt lgkmcnt(0)
	v_mfma_f32_16x16x32_bf16 v[62:65], v[122:125], v[182:185], v[62:65]
	v_mfma_f32_16x16x32_bf16 v[58:61], v[138:141], v[182:185], v[58:61]
	v_mfma_f32_16x16x32_bf16 v[46:49], v[122:125], v[190:193], v[46:49]
	v_mfma_f32_16x16x32_bf16 v[42:45], v[138:141], v[190:193], v[42:45]
	v_mfma_f32_16x16x32_bf16 v[30:33], v[122:125], v[204:207], v[30:33]
	v_mfma_f32_16x16x32_bf16 v[26:29], v[138:141], v[204:207], v[26:29]
	v_mfma_f32_16x16x32_bf16 v[14:17], v[122:125], v[228:231], v[14:17]
	v_mfma_f32_16x16x32_bf16 v[10:13], v[138:141], v[228:231], v[10:13]
	v_mfma_f32_16x16x32_bf16 v[62:65], v[134:137], v[186:189], v[62:65]
	v_mfma_f32_16x16x32_bf16 v[58:61], v[142:145], v[186:189], v[58:61]
	v_mfma_f32_16x16x32_bf16 v[46:49], v[134:137], v[200:203], v[46:49]
	v_mfma_f32_16x16x32_bf16 v[42:45], v[142:145], v[200:203], v[42:45]
	v_mfma_f32_16x16x32_bf16 v[30:33], v[134:137], v[224:227], v[30:33]
	v_mfma_f32_16x16x32_bf16 v[26:29], v[142:145], v[224:227], v[26:29]
	v_mfma_f32_16x16x32_bf16 v[14:17], v[134:137], v[232:235], v[14:17]
	v_mfma_f32_16x16x32_bf16 v[10:13], v[142:145], v[232:235], v[10:13]
	s_setprio 0
	s_setprio 1
	v_mfma_f32_16x16x32_bf16 v[54:57], v[146:149], v[182:185], v[54:57]
	v_mfma_f32_16x16x32_bf16 v[50:53], v[154:157], v[182:185], v[50:53]
	v_mfma_f32_16x16x32_bf16 v[38:41], v[146:149], v[190:193], v[38:41]
	v_mfma_f32_16x16x32_bf16 v[34:37], v[154:157], v[190:193], v[34:37]
	v_mfma_f32_16x16x32_bf16 v[22:25], v[146:149], v[204:207], v[22:25]
	v_mfma_f32_16x16x32_bf16 v[18:21], v[154:157], v[204:207], v[18:21]
	v_mfma_f32_16x16x32_bf16 v[6:9], v[146:149], v[228:231], v[6:9]
	v_mfma_f32_16x16x32_bf16 v[2:5], v[154:157], v[228:231], v[2:5]
	v_mfma_f32_16x16x32_bf16 v[54:57], v[150:153], v[186:189], v[54:57]
	v_mfma_f32_16x16x32_bf16 v[50:53], v[178:181], v[186:189], v[50:53]
	v_mfma_f32_16x16x32_bf16 v[38:41], v[150:153], v[200:203], v[38:41]
	v_mfma_f32_16x16x32_bf16 v[34:37], v[178:181], v[200:203], v[34:37]
	v_mfma_f32_16x16x32_bf16 v[22:25], v[150:153], v[224:227], v[22:25]
	v_mfma_f32_16x16x32_bf16 v[18:21], v[178:181], v[224:227], v[18:21]
	v_mfma_f32_16x16x32_bf16 v[6:9], v[150:153], v[232:235], v[6:9]
	v_mfma_f32_16x16x32_bf16 v[2:5], v[178:181], v[232:235], v[2:5]
	s_setprio 0
	s_barrier
	s_add_u32 s6, s6, 0x100
	s_addc_u32 s7, s7, 0
	s_add_u32 s26, s26, 0x100
	s_addc_u32 s27, s27, 0
	s_cmp_ge_u32 s47, s40
	s_mov_b32 s24, s47
	s_cbranch_scc0 .LBB0_1344
